# attention KV loop: K/V LDS tiles double-buffered in free LDS, loop-top workgroup barrier removed (one barrier per KV block)
# speedup vs baseline: 1.0030x; 1.0030x over previous
; __device__ __forceinline__ void attn_tile(const Params& p, int l, int tile, unsigned char* smem) {
;     ...
;   const int ntile = nb + 4;
;   const int lr = tid >> 3, lc = tid & 7;
;   uint4 kr0, kr1, vr0, vr1;
;     ...
;   KVLOAD(0);
;   for (int kt = 0; kt < ntile; ++kt) {
;     __syncthreads();
;     *(uint4*)(Ks + lr * 72 + lc * 8) = kr0;
;     *(uint4*)(Ks + (lr + 32) * 72 + lc * 8) = kr1;
;     VTSTORE(vr0, lr);
;     VTSTORE(vr1, lr + 32);
;     __syncthreads();
;     if (kt + 1 < ntile) KVLOAD(kt + 1);
.LBB0_523:
	s_andn2_b64 vcc, exec, s[46:47]
	s_cbranch_vccnz .LBB0_545
	s_mul_i32 s46, s49, 0x56
	s_bfe_u32 s47, s46, 0x1000f
	s_bfe_u32 s46, s46, 0x80008
	s_add_i32 s46, s46, s47
	s_sext_i32_i8 s46, s46
	s_lshl_b32 s46, s46, 6
	s_ashr_i32 s47, s46, 31
	s_add_i32 s64, s59, 4
	v_ashrrev_i32_e32 v100, 3, v4
	s_add_u32 s44, s44, s51
	v_ashrrev_i32_e32 v101, 31, v100
	s_addc_u32 s45, s45, 0
	v_lshl_add_u64 v[6:7], s[44:45], 0, v[100:101]
	v_readlane_b32 s0, v251, 48
	v_lshlrev_b32_e32 v1, 3, v4
	v_lshlrev_b64 v[6:7], 11, v[6:7]
	v_readlane_b32 s8, v251, 56
	v_readlane_b32 s9, v251, 57
	v_and_b32_e32 v1, 56, v1
	s_lshl_b64 s[44:45], s[46:47], 1
	v_lshl_add_u64 v[6:7], s[8:9], 0, v[6:7]
	v_lshlrev_b32_e32 v4, 1, v1
	v_lshl_add_u64 v[6:7], v[6:7], 0, s[44:45]
	v_mov_b32_e32 v5, v164
	v_lshl_add_u64 v[6:7], v[6:7], 0, v[4:5]
	v_add_co_u32_e32 v8, vcc, s27, v6
	s_add_u32 s46, s56, s50
	s_nop 0
	v_addc_co_u32_e32 v9, vcc, 0, v7, vcc
	global_load_dwordx4 v[52:55], v[8:9], off offset:1024
	global_load_dwordx4 v[60:63], v[8:9], off offset:768
	global_load_dwordx4 v[48:51], v[6:7], off offset:1024
	global_load_dwordx4 v[56:59], v[6:7], off offset:768
	s_addc_u32 s47, s57, 0
	s_add_u32 s65, s46, 0x100
	s_movk_i32 s0, 0x1200
	s_addc_u32 s66, s47, 0
	v_mul_lo_u32 v3, v3, s0
	v_mul_u32_u24_e32 v1, 0x48, v1
	s_add_u32 s44, s8, s44
	v_add_u32_e32 v3, 0, v3
	v_lshlrev_b32_e32 v6, 1, v100
	v_lshlrev_b32_e32 v1, 1, v1
	s_addc_u32 s45, s9, s45
	s_addk_i32 s48, 0xff4f
	v_add_u32_e32 v7, 0, v4
	s_movk_i32 s0, 0x90
	v_add3_u32 v109, 0, v6, v1
	v_add3_u32 v110, 0, v1, v6
	v_add_u32_e32 v1, 0, v0
	v_lshl_add_u32 v6, v104, 1, v3
	v_add_u32_e32 v3, v3, v0
	v_lshl_add_u64 v[102:103], s[44:45], 0, v[4:5]
	v_add3_u32 v0, s48, v98, v105
	v_add_u32_e32 v4, s50, v104
	v_mul_lo_u32 v8, v100, s0
	v_mul_u32_u24_e32 v9, 0x90, v104
	v_mul_u32_u24_e32 v2, 0x240, v2
	v_sub_u32_e32 v111, v0, v4
	v_mov_b32_e32 v0, 0
	v_mov_b32_e32 v116, 1.0
	s_mov_b32 s67, -4
	s_mov_b32 s68, 64
	v_add_u32_e32 v112, v7, v8
	v_add_u32_e32 v113, v3, v9
	v_add_u32_e32 v114, v1, v9
	v_add_u32_e32 v115, v6, v2
	s_waitcnt vmcnt(8)
	v_mov_b32_e32 v130, v117
	v_mov_b32_e32 v131, v117
	v_mov_b32_e32 v132, v117
	v_mov_b32_e32 v126, v117
	v_mov_b32_e32 v127, v117
	v_mov_b32_e32 v128, v117
	v_mov_b32_e32 v129, v117
	v_mov_b32_e32 v123, 1.0
	v_mov_b32_e32 v124, 1.0
	v_mov_b32_e32 v122, 1.0
	v_mov_b32_e32 v121, 1.0
	v_mov_b32_e32 v120, 1.0
	v_mov_b32_e32 v118, 1.0
	v_mov_b32_e32 v119, 1.0
	v_mov_b32_e32 v1, v0
	v_mov_b32_e32 v2, v0
	v_mov_b32_e32 v3, v0
	v_mov_b32_e32 v4, v0
	v_mov_b32_e32 v5, v0
	v_mov_b32_e32 v6, v0
	v_mov_b32_e32 v7, v0
	v_mov_b32_e32 v8, v0
	v_mov_b32_e32 v9, v0
	v_mov_b32_e32 v10, v0
	v_mov_b32_e32 v11, v0
	v_mov_b32_e32 v12, v0
	v_mov_b32_e32 v13, v0
	v_mov_b32_e32 v14, v0
	v_mov_b32_e32 v15, v0
	v_mov_b32_e32 v24, v0
	v_mov_b32_e32 v25, v0
	v_mov_b32_e32 v26, v0
	v_mov_b32_e32 v27, v0
	v_mov_b32_e32 v16, v0
	v_mov_b32_e32 v17, v0
	v_mov_b32_e32 v18, v0
	v_mov_b32_e32 v19, v0
	v_mov_b32_e32 v20, v0
	v_mov_b32_e32 v21, v0
	v_mov_b32_e32 v22, v0
	v_mov_b32_e32 v23, v0
	v_mov_b32_e32 v28, v0
	v_mov_b32_e32 v29, v0
	v_mov_b32_e32 v30, v0
	v_mov_b32_e32 v31, v0
	v_readlane_b32 s1, v251, 49
	v_readlane_b32 s2, v251, 50
	v_readlane_b32 s3, v251, 51
	v_readlane_b32 s4, v251, 52
	v_readlane_b32 s5, v251, 53
	v_readlane_b32 s6, v251, 54
	v_readlane_b32 s7, v251, 55
	v_readlane_b32 s10, v251, 58
	v_readlane_b32 s11, v251, 59
	v_readlane_b32 s12, v251, 60
	v_readlane_b32 s13, v251, 61
	v_readlane_b32 s14, v251, 62
	v_readlane_b32 s15, v251, 63
	v_add_u32_e32 v112, 0x9000, v112
	v_add_u32_e32 v114, 0x9000, v114
	v_add_u32_e32 v109, 0x9000, v109
	v_add_u32_e32 v110, 0x9000, v110
	s_mov_b32 s101, 0xffff7000
.LBB0_525:
	v_add_u32_e32 v112, s101, v112
	v_add_u32_e32 v114, s101, v114
	v_add_u32_e32 v109, s101, v109
	v_add_u32_e32 v110, s101, v110
	s_sub_i32 s101, 0, s101
	s_add_i32 s44, s67, 5
	s_cmp_ge_i32 s44, s64
	s_waitcnt vmcnt(0)
	ds_write_b128 v112, v[56:59]
	ds_write_b128 v112, v[60:63] offset:4608
	ds_write_b16 v109, v48 offset:9216
	ds_write_b16_d16_hi v109, v48 offset:9360
	ds_write_b16 v109, v49 offset:9504
	ds_write_b16_d16_hi v109, v49 offset:9648
	ds_write_b16 v109, v50 offset:9792
	ds_write_b16_d16_hi v109, v50 offset:9936
	ds_write_b16 v109, v51 offset:10080
	ds_write_b16_d16_hi v109, v51 offset:10224
	ds_write_b16 v110, v52 offset:9280
	ds_write_b16_d16_hi v110, v52 offset:9424
	ds_write_b16 v110, v53 offset:9568
	ds_write_b16_d16_hi v110, v53 offset:9712
	ds_write_b16 v110, v54 offset:9856
	ds_write_b16_d16_hi v110, v54 offset:10000
	ds_write_b16 v110, v55 offset:10144
	ds_write_b16_d16_hi v110, v55 offset:10288
	s_waitcnt lgkmcnt(0)
	s_barrier
	s_cbranch_scc1 .LBB0_527
	s_cmp_lt_i32 s44, s59
	s_cselect_b64 s[44:45], -1, 0
	s_and_b64 s[44:45], s[44:45], exec
	s_cselect_b32 s44, 0, s59
	s_cselect_b32 s45, s66, s57
	s_cselect_b32 s46, s65, s56
	s_lshl_b32 s44, s44, 6
	s_sub_i32 s44, s68, s44
	s_add_u32 s44, s44, s46
	s_addc_u32 s45, 0, s45
	v_lshl_add_u64 v[48:49], s[44:45], 0, v[100:101]
	v_lshlrev_b64 v[48:49], 11, v[48:49]
	v_lshl_add_u64 v[52:53], v[102:103], 0, v[48:49]
	global_load_dwordx4 v[56:59], v[52:53], off offset:768
	global_load_dwordx4 v[48:51], v[52:53], off offset:1024
	v_add_co_u32_e32 v52, vcc, 0x10000, v52
	s_nop 1
	v_addc_co_u32_e32 v53, vcc, 0, v53, vcc
	global_load_dwordx4 v[60:63], v[52:53], off offset:768
	s_nop 0
	global_load_dwordx4 v[52:55], v[52:53], off offset:1024
